# one-way cross-XCD barrier level with the XCD leader's spin bound raised to the baseline's 2^24 (otherwise identical to the previous version)
# speedup vs baseline: 1.0067x; 1.0067x over previous
; __device__ __forceinline__ unsigned xb_ld(unsigned* p)              { return __hip_atomic_load(p, __ATOMIC_RELAXED, __HIP_MEMORY_SCOPE_AGENT); }
; #define XB_SPIN(cond, bar) do { unsigned _sp = 0; while (cond) { __builtin_amdgcn_s_sleep(1); \
;     if ((++_sp & 255u) == 0u) { if (xb_ld(&(bar)[XB_TMO])) break; if (_sp > XB_SPIN_CAP) { atomicAdd(&(bar)[XB_TMO], 1u); break; } } } } while (0)
; __device__ __forceinline__ void xcd_barrier(unsigned* bar, volatile LAS unsigned* st) {
;     ...
;             else XB_SPIN(xb_ld(&bar[XB_TOPGEN]) == tg, bar);
.Lxb_lspin:
	global_load_dword v4, v1, s[14:15] sc1
	s_add_i32 s4, s4, 1
	s_waitcnt vmcnt(0)
	v_cmp_le_u32_e32 vcc, v3, v4
	s_cbranch_vccnz .Lxb_ldone
	s_cmp_lt_u32 s4, 0x1000001
	s_cbranch_scc0 .Lxb_ldone
	s_sleep 1
	s_branch .Lxb_lspin
